# y flush moved to the end of the helper waves' chunk pipeline (both halves, at normal priority)
# baseline (speedup 1.0000x reference)
.LBB0_670:
	s_branch .LBB0_672
	s_cmp_eq_u32 s65, 0
	s_cbranch_scc1 .LBB0_672
	s_and_b32 s22, s64, 0x800
	v_lshl_add_u32 v21, s22, 2, v68
	v_cndmask_b32_e64 v76, v71, v70, s[4:5]
	ds_read_b128 v[72:75], v21
	v_ashrrev_i32_e32 v77, 31, v76
	v_lshl_add_u64 v[76:77], v[76:77], 0, s[40:41]
	v_lshlrev_b64 v[76:77], 12, v[76:77]
	v_lshl_add_u64 v[76:77], v[54:55], 0, v[76:77]
	s_waitcnt lgkmcnt(0)
	global_store_dwordx4 v[76:77], v[72:75], off

.Lmy_f_hlp:
	s_setprio 3
	s_cmp_eq_u32 s65, 63
	s_cbranch_scc0 .Lmy_f_hl2
	s_setprio 0
	s_cmp_eq_u32 s65, 0
	s_cbranch_scc1 .Lmy_f_nofl_a
	s_and_b32 s96, s64, 0x800
	v_lshl_add_u32 v21, s96, 2, v68
	v_cndmask_b32_e64 v76, v71, v70, s[4:5]
	ds_read_b128 v[72:75], v21
	v_ashrrev_i32_e32 v77, 31, v76
	v_lshl_add_u64 v[76:77], v[76:77], 0, s[40:41]
	v_lshlrev_b64 v[76:77], 12, v[76:77]
	v_lshl_add_u64 v[76:77], v[54:55], 0, v[76:77]
	v_subrev_u32_e32 v70, 16, v70
	v_add_u32_e32 v71, 16, v71
	v_lshl_add_u32 v21, s96, 2, v68
	v_add_u32_e32 v21, 0xfffff000, v21
	v_cndmask_b32_e64 v84, v71, v70, s[4:5]
	ds_read_b128 v[80:83], v21
	v_ashrrev_i32_e32 v85, 31, v84
	v_lshl_add_u64 v[84:85], v[84:85], 0, s[40:41]
	v_lshlrev_b64 v[84:85], 12, v[84:85]
	v_lshl_add_u64 v[84:85], v[54:55], 0, v[84:85]
	v_add_u32_e32 v70, 16, v70
	v_subrev_u32_e32 v71, 16, v71
	s_waitcnt lgkmcnt(0)
	global_store_dwordx4 v[76:77], v[72:75], off
	global_store_dwordx4 v[84:85], v[80:83], off
.Lmy_f_nofl_a:
	s_branch .LBB0_655
.Lmy_f_hl2:
	s_bfe_u32 s100, s62, 0x20006
	s_lshl_b32 s100, s100, 2
	s_add_i32 s101, s100, -16
	s_add_i32 s100, s100, -12
	s_cmp_lg_u32 s65, 0
	s_cbranch_scc1 .Lmy_f_nol2
	v_add_u32_e32 v70, s101, v70
	v_subrev_u32_e32 v71, s101, v71
	v_add_u32_e32 v21, 64, v70
	v_subrev_u32_e32 v26, 64, v71
	v_cndmask_b32_e64 v32, v26, v21, s[4:5]
	v_ashrrev_i32_e32 v33, 31, v32
	v_lshl_add_u64 v[44:45], v[32:33], 0, s[40:41]
	v_mad_u64_u32 v[46:47], s[96:97], v44, s56, v[50:51]
	v_mad_i32_i24 v47, v45, s56, v47
	v_mov_b32_e32 v166, v46
	v_mov_b32_e32 v167, v47
	global_load_dwordx2 v[26:27], v[46:47], off
	v_mov_b32_e32 v30, v20
	v_mov_b32_e32 v31, v20
	v_cmp_lt_i32_e64 s[96:97], 0, v32
	v_mov_b64_e32 v[28:29], v[30:31]
	s_and_saveexec_b64 s[24:25], s[96:97]
	s_cbranch_execz .Lmy_f_k659
	v_add_co_u32_e32 v28, vcc, 0xfffff000, v46
	s_nop 1
	v_addc_co_u32_e32 v29, vcc, -1, v47, vcc
	global_load_dwordx2 v[28:29], v[28:29], off offset:-2048

.Lmy_ck_drE_h:
	s_waitcnt lgkmcnt(0)
	s_bfe_u32 s96, s62, 0x20006
	s_and_b32 s97, s96, 1
	s_mul_i32 s97, s97, 0x2700
	s_mov_b32 s101, 0x1c000
	s_mov_b32 s100, 0x6100
	s_bitcmp0_b32 s65, 0
	s_cselect_b32 s101, 0xe000, s101
	s_cselect_b32 s100, 0x4e00, s100
	s_cmp_gt_u32 s96, 1
	s_cselect_b32 s100, s100, 0
	s_add_i32 s97, s97, s101
	s_add_i32 s97, s97, s100
	s_mov_b32 s96, s97
	v_and_b32_e32 v72, 3, v233
	v_lshrrev_b32_e32 v73, 2, v233
	v_lshlrev_b32_e32 v72, 2, v72
	v_lshl_add_u32 v72, v73, 8, v72
	v_lshl_add_u32 v72, v234, 6, v72
	s_add_i32 s97, s96, 0x1000
	v_add_u32_e32 v78, s97, v72
	v_xor_b32_e32 v79, v224, v234
	v_lshl_add_u32 v79, v79, 4, s96
	ds_read_b128 v[96:99], v79
	ds_read_b128 v[100:103], v79 offset:1024
	ds_read_b128 v[104:107], v79 offset:2048
	ds_read_b128 v[108:111], v79 offset:3072
	ds_read_b32 v80, v78
	ds_read_b32 v81, v78 offset:16
	ds_read_b32 v82, v78 offset:32
	ds_read_b32 v83, v78 offset:48
	ds_read_b32 v84, v78 offset:1024
	ds_read_b32 v85, v78 offset:1040
	ds_read_b32 v86, v78 offset:1056
	ds_read_b32 v87, v78 offset:1072
	ds_read_b32 v88, v78 offset:2048
	ds_read_b32 v89, v78 offset:2064
	ds_read_b32 v90, v78 offset:2080
	ds_read_b32 v91, v78 offset:2096
	ds_read_b32 v92, v78 offset:3072
	ds_read_b32 v93, v78 offset:3088
	ds_read_b32 v94, v78 offset:3104
	ds_read_b32 v95, v78 offset:3120
	v_lshl_add_u32 v74, v224, 2, s96
	ds_write_b32 v74, v235 offset:9728
	v_add_u32_e32 v75, -1, v233
	v_mov_b32_e32 v76, -1
	v_cndmask_b32_e64 v75, v76, v75, s[98:99]
	v_cmp_lt_u32_e64 s[100:101], 7, v233
	v_add_u32_e32 v76, -8, v233
	v_and_b32_e32 v77, 1, v234
	v_cndmask_b32_e64 v75, v75, v76, s[100:101]
	v_lshlrev_b32_e32 v77, 2, v77
	v_sub_u32_e32 v76, v75, v77
	v_lshlrev_b32_e32 v77, 2, v234
	v_sub_u32_e32 v77, v233, v77
	v_add_u32_e32 v77, -1, v77
	s_waitcnt lgkmcnt(15)
	v_mfma_f32_16x16x4_f32 v[244:247], v80, v96, 0
	v_mfma_f32_16x16x4_f32 v[240:243], v81, v97, 0
	s_waitcnt lgkmcnt(14)
	v_mfma_f32_16x16x4_f32 v[244:247], v82, v98, v[244:247]
	s_waitcnt lgkmcnt(13)
	v_mfma_f32_16x16x4_f32 v[240:243], v83, v99, v[240:243]
	s_waitcnt lgkmcnt(12)
	v_mfma_f32_16x16x4_f32 v[244:247], v84, v100, v[244:247]
	s_waitcnt lgkmcnt(11)
	v_mfma_f32_16x16x4_f32 v[240:243], v85, v101, v[240:243]
	s_waitcnt lgkmcnt(10)
	v_mfma_f32_16x16x4_f32 v[244:247], v86, v102, v[244:247]
	s_waitcnt lgkmcnt(9)
	v_mfma_f32_16x16x4_f32 v[240:243], v87, v103, v[240:243]
	s_waitcnt lgkmcnt(8)
	v_mfma_f32_16x16x4_f32 v[244:247], v88, v104, v[244:247]
	s_waitcnt lgkmcnt(7)
	v_mfma_f32_16x16x4_f32 v[240:243], v89, v105, v[240:243]
	s_waitcnt lgkmcnt(6)
	v_mfma_f32_16x16x4_f32 v[244:247], v90, v106, v[244:247]
	s_waitcnt lgkmcnt(5)
	v_mfma_f32_16x16x4_f32 v[240:243], v91, v107, v[240:243]
	s_waitcnt lgkmcnt(4)
	v_mfma_f32_16x16x4_f32 v[244:247], v92, v108, v[244:247]
	s_waitcnt lgkmcnt(3)
	v_mfma_f32_16x16x4_f32 v[240:243], v93, v109, v[240:243]
	s_waitcnt lgkmcnt(2)
	v_mfma_f32_16x16x4_f32 v[244:247], v94, v110, v[244:247]
	s_waitcnt lgkmcnt(1)
	v_mfma_f32_16x16x4_f32 v[240:243], v95, v111, v[240:243]
	s_nop 9
	v_add_f32_e32 v244, v244, v240
	v_add_f32_e32 v245, v245, v241
	v_add_f32_e32 v246, v246, v242
	v_add_f32_e32 v247, v247, v243
	v_cmp_le_i32_e64 s[96:97], 0, v76
	v_cmp_le_i32_e64 s[100:101], 1, v76
	s_nop 0
	v_cndmask_b32_e64 v128, 0, v244, s[96:97]
	v_cndmask_b32_e64 v129, 0, v245, s[100:101]
	v_cmp_le_i32_e64 s[96:97], 2, v76
	v_cmp_le_i32_e64 s[100:101], 3, v76
	s_nop 0
	v_cndmask_b32_e64 v130, 0, v246, s[96:97]
	v_cndmask_b32_e64 v131, 0, v247, s[100:101]
	s_bfe_u32 s96, s62, 0x20006
	s_and_b32 s97, s96, 1
	s_mul_i32 s97, s97, 0x2700
	s_mov_b32 s101, 0x1c000
	s_mov_b32 s100, 0x6100
	s_bitcmp0_b32 s65, 0
	s_cselect_b32 s101, 0xe000, s101
	s_cselect_b32 s100, 0x4e00, s100
	s_cmp_gt_u32 s96, 1
	s_cselect_b32 s100, s100, 0
	s_add_i32 s97, s97, s101
	s_add_i32 s97, s97, s100
	v_xor_b32_e32 v74, v224, v234
	v_lshl_add_u32 v74, v74, 4, s97
	ds_write_b128 v74, v[128:131] offset:8448
	v_lshlrev_b32_e32 v75, 7, v234
	v_lshl_add_u32 v75, v233, 2, v75
	v_add_u32_e32 v75, s97, v75
	v_cmp_le_i32_e64 s[96:97], 0, v77
	v_cmp_le_i32_e64 s[100:101], 1, v77
	s_nop 0
	v_cndmask_b32_e64 v132, 0, v244, s[96:97]
	v_cndmask_b32_e64 v133, 0, v245, s[100:101]
	v_cmp_le_i32_e64 s[96:97], 2, v77
	v_cmp_le_i32_e64 s[100:101], 3, v77
	s_nop 0
	v_cndmask_b32_e64 v134, 0, v246, s[96:97]
	v_cndmask_b32_e64 v135, 0, v247, s[100:101]
	s_mov_b64 exec, 0x00ff00ff
	ds_write_b32 v75, v132 offset:9472
	ds_write_b32 v75, v133 offset:9504
	ds_write_b32 v75, v134 offset:9536
	ds_write_b32 v75, v135 offset:9568
	s_mov_b64 exec, -1
	s_setprio 0
	s_cmp_eq_u32 s65, 0
	s_cbranch_scc1 .Lmy_f_nofl_b
	s_and_b32 s96, s64, 0x800
	v_lshl_add_u32 v21, s96, 2, v68
	v_cndmask_b32_e64 v76, v71, v70, s[4:5]
	ds_read_b128 v[72:75], v21
	v_ashrrev_i32_e32 v77, 31, v76
	v_lshl_add_u64 v[76:77], v[76:77], 0, s[40:41]
	v_lshlrev_b64 v[76:77], 12, v[76:77]
	v_lshl_add_u64 v[76:77], v[54:55], 0, v[76:77]
	v_subrev_u32_e32 v70, 16, v70
	v_add_u32_e32 v71, 16, v71
	v_lshl_add_u32 v21, s96, 2, v68
	v_add_u32_e32 v21, 0xfffff000, v21
	v_cndmask_b32_e64 v84, v71, v70, s[4:5]
	ds_read_b128 v[80:83], v21
	v_ashrrev_i32_e32 v85, 31, v84
	v_lshl_add_u64 v[84:85], v[84:85], 0, s[40:41]
	v_lshlrev_b64 v[84:85], 12, v[84:85]
	v_lshl_add_u64 v[84:85], v[54:55], 0, v[84:85]
	v_add_u32_e32 v70, 16, v70
	v_subrev_u32_e32 v71, 16, v71
	s_waitcnt lgkmcnt(0)
	global_store_dwordx4 v[76:77], v[72:75], off
	global_store_dwordx4 v[84:85], v[80:83], off
.Lmy_f_nofl_b:
	s_branch .LBB0_655
	s_nop 0
	s_nop 0
	s_nop 0
	s_nop 0
	s_nop 0
	s_nop 0
	s_nop 0
	s_nop 0
	s_nop 0
	s_nop 0
	s_nop 0
	s_nop 0
	s_nop 0
	s_nop 0
	s_nop 0
	s_nop 0
	s_nop 0
	s_nop 0
	s_nop 0
	s_nop 0
	s_nop 0
	s_nop 0
	s_nop 0
	s_nop 0
	s_nop 0
	s_nop 0
	s_nop 0
	s_nop 0
	s_nop 0
	s_nop 0
	s_nop 0
	s_nop 0
	s_nop 0
	s_nop 0
	s_nop 0
	s_nop 0
	s_nop 0
	s_nop 0
	s_nop 0
	s_nop 0
	s_nop 0
	s_nop 0
	s_nop 0
	s_nop 0
	s_nop 0
	s_nop 0
	s_nop 0
	s_nop 0
	s_nop 0
	s_nop 0
	s_nop 0
	s_nop 0
	s_nop 0
	s_nop 0
